# memory attention: second row-block Q fragments prefetched with the first; pool/conv to dilated-attention hand-over without store drain
# speedup vs baseline: 1.0095x; 1.0025x over previous
.LBB0_132:
	v_writelane_b32 v253, s46, 39
	v_writelane_b32 v253, s38, 40
	v_mov_b32_e32 v10, v216
	s_and_b32 s44, s14, 0xf00
	v_writelane_b32 v253, s39, 41
	v_writelane_b32 v253, s37, 42
	s_waitcnt lgkmcnt(0)
	v_bfe_u32 v2, v10, 4, 2
	v_readlane_b32 s0, v253, 25
	v_readlane_b32 s1, v253, 26
	s_ashr_i32 s0, s0, 4
	v_readlane_b32 s2, v253, 22
	v_and_b32_e32 v137, 15, v10
	s_mul_i32 s1, s0, 12
	v_readlane_b32 s3, v253, 23
	v_lshlrev_b32_e32 v134, 3, v2
	s_add_i32 s1, s1, s2
	v_cmp_le_u32_e64 s[2:3], v134, v137
	v_or_b32_e32 v11, 0x80, v137
	v_or_b32_e32 v185, 0x81, v134
	v_writelane_b32 v253, s2, 43
	v_or_b32_e32 v186, 0x82, v134
	v_or_b32_e32 v187, 0x83, v134
	v_writelane_b32 v253, s3, 44
	v_cmp_le_u32_e64 s[2:3], v185, v11
	v_or_b32_e32 v188, 0x84, v134
	v_or_b32_e32 v189, 0x85, v134
	v_writelane_b32 v253, s2, 45
	v_or_b32_e32 v190, 0x86, v134
	v_or_b32_e32 v191, 0x87, v134
	v_writelane_b32 v253, s3, 46
	v_cmp_le_u32_e64 s[2:3], v186, v11
	v_or_b32_e32 v4, 16, v137
	v_lshlrev_b32_e32 v3, 1, v10
	v_writelane_b32 v253, s2, 47
	v_and_b32_e32 v152, 24, v3
	v_or_b32_e32 v3, 1, v134
	v_writelane_b32 v253, s3, 48
	v_cmp_le_u32_e64 s[2:3], v187, v11
	v_or_b32_e32 v154, 2, v134
	v_or_b32_e32 v155, 3, v134
	v_writelane_b32 v253, s2, 49
	v_or_b32_e32 v156, 4, v134
	v_or_b32_e32 v157, 5, v134
	v_writelane_b32 v253, s3, 50
	v_cmp_le_u32_e64 s[2:3], v188, v11
	v_or_b32_e32 v158, 6, v134
	v_or_b32_e32 v159, 7, v134
	v_writelane_b32 v253, s2, 51
	v_or_b32_e32 v184, 0x80, v134
	v_or_b32_e32 v5, 0x90, v137
	v_writelane_b32 v253, s3, 52
	v_cmp_le_u32_e64 s[2:3], v189, v11
	s_lshl_b32 s0, s0, 12
	s_or_b32 s0, s0, s44
	v_writelane_b32 v253, s2, 53
	s_ashr_i32 s23, s22, 31
	v_ashrrev_i32_e32 v0, 5, v10
	v_writelane_b32 v253, s3, 54
	v_cmp_le_u32_e64 s[2:3], v190, v11
	v_and_b32_e32 v147, -2, v0
	v_lshlrev_b32_e32 v0, 6, v137
	v_writelane_b32 v253, s2, 55
	v_cmp_ge_u32_e64 s[66:67], v3, v137
	v_lshlrev_b32_e32 v136, 2, v2
	v_writelane_b32 v253, s3, 56
	v_cmp_le_u32_e64 s[2:3], v191, v11
	v_lshlrev_b32_e32 v6, 7, v137
	v_mov_b32_e32 v7, v1
	v_writelane_b32 v253, s2, 57
	v_cmp_ge_u32_e64 s[48:49], v134, v137
	v_cmp_ge_u32_e64 s[68:69], v154, v137
	v_writelane_b32 v253, s3, 58
	v_cmp_ge_u32_e64 s[2:3], v134, v4
	v_cmp_ge_u32_e64 s[70:71], v155, v137
	v_cmp_ge_u32_e64 s[74:75], v156, v137
	v_writelane_b32 v253, s2, 59
	v_cmp_ge_u32_e64 s[76:77], v157, v137
	v_cmp_ge_u32_e64 s[78:79], v158, v137
	v_writelane_b32 v253, s3, 60
	v_cmp_ge_u32_e64 s[2:3], v3, v4
	v_mov_b32_e32 v3, v1
	v_cmp_ge_u32_e64 s[80:81], v159, v137
	v_writelane_b32 v253, s2, 61
	v_mov_b32_e32 v135, v1
	v_and_b32_e32 v153, 3, v10
	v_writelane_b32 v253, s3, 62
	v_cmp_ge_u32_e64 s[2:3], v154, v4
	v_or_b32_e32 v160, 32, v134
	v_or_b32_e32 v161, 33, v134
	v_writelane_b32 v253, s2, 63
	v_or_b32_e32 v162, 34, v134
	v_or_b32_e32 v163, 35, v134
	v_writelane_b32 v255, s3, 0
	v_cmp_ge_u32_e64 s[2:3], v155, v4
	v_or_b32_e32 v164, 36, v134
	v_or_b32_e32 v165, 37, v134
	v_writelane_b32 v255, s2, 1
	v_or_b32_e32 v166, 38, v134
	v_or_b32_e32 v167, 39, v134
	v_writelane_b32 v255, s3, 2
	v_cmp_ge_u32_e64 s[2:3], v156, v4
	v_or_b32_e32 v168, 64, v134
	v_or_b32_e32 v169, 0x41, v134
	v_writelane_b32 v255, s2, 3
	v_or_b32_e32 v170, 0x42, v134
	v_or_b32_e32 v171, 0x43, v134
	v_writelane_b32 v255, s3, 4
	v_cmp_ge_u32_e64 s[2:3], v157, v4
	v_or_b32_e32 v172, 0x44, v134
	v_or_b32_e32 v173, 0x45, v134
	v_writelane_b32 v255, s2, 5
	v_or_b32_e32 v174, 0x46, v134
	v_or_b32_e32 v175, 0x47, v134
	v_writelane_b32 v255, s3, 6
	v_cmp_ge_u32_e64 s[2:3], v158, v4
	v_or_b32_e32 v176, 0x60, v134
	v_or_b32_e32 v177, 0x61, v134
	v_writelane_b32 v255, s2, 7
	v_or_b32_e32 v178, 0x62, v134
	v_or_b32_e32 v179, 0x63, v134
	v_writelane_b32 v255, s3, 8
	v_cmp_ge_u32_e64 s[2:3], v159, v4
	v_or_b32_e32 v180, 0x64, v134
	v_or_b32_e32 v181, 0x65, v134
	v_writelane_b32 v255, s2, 9
	v_or_b32_e32 v182, 0x66, v134
	v_or_b32_e32 v183, 0x67, v134
	v_writelane_b32 v255, s3, 10
	v_cmp_le_u32_e64 s[2:3], v184, v5
	s_mov_b32 s41, 0
	v_ashrrev_i32_e32 v192, 31, v10
	v_writelane_b32 v255, s2, 11
	s_mov_b64 s[34:35], 0xc000
	s_nop 0
	v_writelane_b32 v255, s3, 12
	v_cmp_le_u32_e64 s[2:3], v185, v5
	s_barrier
	s_nop 0
	v_writelane_b32 v255, s2, 13
	s_nop 1
	v_writelane_b32 v255, s3, 14
	v_cmp_le_u32_e64 s[2:3], v186, v5
	s_nop 1
	v_writelane_b32 v255, s2, 15
	s_nop 1
	v_writelane_b32 v255, s3, 16
	v_cmp_le_u32_e64 s[2:3], v187, v5
	s_nop 1
	v_writelane_b32 v255, s2, 17
	s_nop 1
	v_writelane_b32 v255, s3, 18
	v_cmp_le_u32_e64 s[2:3], v188, v5
	s_nop 1
	v_writelane_b32 v255, s2, 19
	s_nop 1
	v_writelane_b32 v255, s3, 20
	v_cmp_le_u32_e64 s[2:3], v189, v5
	s_nop 1
	v_writelane_b32 v255, s2, 21
	s_nop 1
	v_writelane_b32 v255, s3, 22
	v_cmp_le_u32_e64 s[2:3], v190, v5
	s_nop 1
	v_writelane_b32 v255, s2, 23
	s_nop 1
	v_writelane_b32 v255, s3, 24
	v_cmp_le_u32_e64 s[2:3], v191, v5
	s_nop 1
	v_writelane_b32 v255, s2, 25
	s_nop 1
	v_writelane_b32 v255, s3, 26
	v_writelane_b32 v255, s0, 27
	v_writelane_b32 v255, s22, 29
	v_cmp_eq_u32_e64 s[2:3], 0, v2
	s_add_i32 s0, s1, 8
	v_writelane_b32 v255, s23, 30
	v_writelane_b32 v255, s2, 31
	v_lshlrev_b32_e32 v2, 4, v2
	s_nop 0
	v_writelane_b32 v255, s3, 32
	v_writelane_b32 v255, s1, 33
	s_ashr_i32 s1, s0, 31
	s_lshl_b64 s[2:3], s[0:1], 12
	v_writelane_b32 v255, s2, 35
	s_lshl_b64 s[0:1], s[0:1], 19
	s_nop 0
	v_writelane_b32 v255, s3, 36
	v_cmp_gt_u32_e64 s[2:3], v134, v137
	s_nop 1
	v_writelane_b32 v255, s2, 37
	s_nop 1
	v_writelane_b32 v255, s3, 38
	s_add_u32 s2, s82, 0xa800000
	s_addc_u32 s3, s83, 0
	s_add_u32 s4, s82, 0xc000000
	s_addc_u32 s5, s83, 0
	v_writelane_b32 v255, s4, 39
	v_lshl_add_u64 v[4:5], s[2:3], 0, v[2:3]
	v_lshl_add_u64 v[8:9], s[2:3], 0, v[6:7]
	v_writelane_b32 v255, s5, 40
	s_add_u32 s4, s82, 0xd800000
	s_addc_u32 s5, s83, 0
	s_add_u32 s6, s82, s11
	s_addc_u32 s7, s83, s10
	s_add_u32 s6, s6, s12
	s_addc_u32 s7, s7, s13
	v_writelane_b32 v255, s6, 41
	s_add_u32 s0, s4, s0
	s_addc_u32 s1, s5, s1
	v_writelane_b32 v255, s7, 42
	v_cmp_gt_u32_e64 s[6:7], v185, v11
	v_lshl_add_u64 v[138:139], s[4:5], 0, v[0:1]
	v_cmp_gt_u32_e64 s[4:5], v186, v11
	v_writelane_b32 v255, s6, 43
	v_cmp_gt_u32_e64 s[2:3], v187, v11
	v_lshl_add_u64 v[140:141], s[0:1], 0, v[0:1]
	v_writelane_b32 v255, s7, 44
	v_writelane_b32 v255, s4, 45
	v_cmp_gt_u32_e64 s[0:1], v188, v11
	v_sub_u32_e32 v0, 0, v147
	v_writelane_b32 v255, s5, 46
	v_writelane_b32 v255, s2, 47
	v_lshl_add_u64 v[142:143], v[4:5], 0, v[6:7]
	v_lshl_add_u64 v[144:145], v[8:9], 0, v[2:3]
	v_writelane_b32 v255, s3, 48
	v_writelane_b32 v255, s0, 49
	v_max_i32_e32 v146, v147, v0
	s_nop 0
	v_writelane_b32 v255, s1, 50
	v_cmp_gt_u32_e64 s[0:1], v189, v11
	s_nop 1
	v_writelane_b32 v255, s0, 51
	s_nop 1
	v_writelane_b32 v255, s1, 52
	v_cmp_gt_u32_e64 s[0:1], v190, v11
	s_nop 1
	v_writelane_b32 v255, s0, 53
	s_nop 1
	v_writelane_b32 v255, s1, 54
	v_cmp_gt_u32_e64 s[0:1], v191, v11
	s_nop 1
	v_writelane_b32 v255, s0, 55
	s_nop 1
	v_writelane_b32 v255, s1, 56
	v_writelane_b32 v255, s48, 57
	s_nop 1
	v_writelane_b32 v255, s49, 58
	v_writelane_b32 v255, s66, 59
	s_nop 1
	v_writelane_b32 v255, s67, 60
	v_writelane_b32 v255, s68, 61
	s_nop 1
	v_writelane_b32 v255, s69, 62
	v_writelane_b32 v255, s70, 63
	s_nop 1
	v_writelane_b32 v254, s71, 0
	v_writelane_b32 v254, s74, 1
	s_nop 1
	v_writelane_b32 v254, s75, 2
	v_writelane_b32 v254, s76, 3
	s_nop 1
	v_writelane_b32 v254, s77, 4
	v_writelane_b32 v254, s78, 5
	s_nop 1
	v_writelane_b32 v254, s79, 6
	v_writelane_b32 v254, s80, 7
	s_nop 1
	v_writelane_b32 v254, s81, 8
	s_branch .LBB0_134

.LBB0_190:
	v_or_b32_e32 v2, s8, v77
	v_ashrrev_i32_e32 v3, 31, v2
	v_lshlrev_b64 v[70:71], 10, v[2:3]
	s_and_b64 vcc, exec, s[0:1]
	s_cbranch_vccz .Lmq_second
	v_lshl_add_u64 v[2:3], v[66:67], 0, v[70:71]
	global_load_dwordx4 v[6:9], v[2:3], off
	global_load_dwordx4 v[10:13], v[2:3], off offset:64
	global_load_dwordx4 v[14:17], v[2:3], off offset:128
	global_load_dwordx4 v[18:21], v[2:3], off offset:192
	v_or_b32_e32 v152, 16, v77
	v_ashrrev_i32_e32 v153, 31, v152
	v_lshlrev_b64 v[152:153], 10, v[152:153]
	v_lshl_add_u64 v[152:153], v[66:67], 0, v[152:153]
	global_load_dwordx4 v[156:159], v[152:153], off
	global_load_dwordx4 v[160:163], v[152:153], off offset:64
	global_load_dwordx4 v[164:167], v[152:153], off offset:128
	global_load_dwordx4 v[168:171], v[152:153], off offset:192
	s_branch .Lmq_qdone
.Lmq_second:
	v_mov_b32_e32 v6, v156
	v_mov_b32_e32 v7, v157
	v_mov_b32_e32 v8, v158
	v_mov_b32_e32 v9, v159
	v_mov_b32_e32 v10, v160
	v_mov_b32_e32 v11, v161
	v_mov_b32_e32 v12, v162
	v_mov_b32_e32 v13, v163
	v_mov_b32_e32 v14, v164
	v_mov_b32_e32 v15, v165
	v_mov_b32_e32 v16, v166
	v_mov_b32_e32 v17, v167
	v_mov_b32_e32 v18, v168
	v_mov_b32_e32 v19, v169
	v_mov_b32_e32 v20, v170
	v_mov_b32_e32 v21, v171
.Lmq_qdone:
	v_mov_b32_e32 v46, 0
	s_xor_b64 s[2:3], s[0:1], -1
	v_mov_b32_e32 v0, 0xff800000
	s_mov_b64 s[0:1], -1
	s_mov_b32 s6, 0
	v_mov_b32_e32 v54, 0
	v_mov_b32_e32 v55, v46
	v_mov_b32_e32 v56, v46
	v_mov_b32_e32 v57, v46
	v_mov_b32_e32 v38, 0
	v_mov_b32_e32 v39, v46
	v_mov_b32_e32 v40, v46
	v_mov_b32_e32 v41, v46
	v_mov_b32_e32 v34, 0
	v_mov_b32_e32 v35, v46
	v_mov_b32_e32 v36, v46
	v_mov_b32_e32 v37, v46
	v_mov_b32_e32 v30, 0
	v_mov_b32_e32 v31, v46
	v_mov_b32_e32 v32, v46
	v_mov_b32_e32 v33, v46
	v_mov_b32_e32 v26, 0
	v_mov_b32_e32 v27, v46
	v_mov_b32_e32 v28, v46
	v_mov_b32_e32 v29, v46
	v_mov_b32_e32 v2, 0
	v_mov_b32_e32 v3, v46
	v_mov_b32_e32 v4, v46
	v_mov_b32_e32 v5, v46
	v_mov_b32_e32 v22, 0
	v_mov_b32_e32 v23, v46
	v_mov_b32_e32 v24, v46
	v_mov_b32_e32 v25, v46
	v_mov_b32_e32 v42, 0
	v_mov_b32_e32 v43, v46
	v_mov_b32_e32 v44, v46
	v_mov_b32_e32 v45, v46
